# final f32 output stores without the nt policy (plain write-back)
# baseline (speedup 1.0000x reference)
.LBB0_2344:
	v_lshl_add_u32 v128, s41, 8, v194
	v_lshl_or_b32 v130, s42, 8, v196
	v_ashrrev_i32_e32 v131, 31, v130
	v_ashrrev_i32_e32 v129, 31, v128
	v_lshl_add_u64 v[132:133], v[130:131], 1, s[12:13]
	v_lshlrev_b64 v[134:135], 11, v[128:129]
	v_or_b32_e32 v228, 16, v128
	v_lshl_add_u64 v[134:135], v[132:133], 0, v[134:135]
	v_ashrrev_i32_e32 v229, 31, v228
	global_load_dwordx4 v[200:203], v[134:135], off
	global_load_dwordx4 v[204:207], v[134:135], off offset:256
	v_lshlrev_b64 v[134:135], 11, v[228:229]
	v_lshl_add_u64 v[134:135], v[132:133], 0, v[134:135]
	global_load_dwordx4 v[208:211], v[134:135], off
	v_or_b32_e32 v192, 32, v128
	v_ashrrev_i32_e32 v193, 31, v192
	global_load_dwordx4 v[212:215], v[134:135], off offset:256
	v_lshlrev_b64 v[182:183], 2, v[130:131]
	v_lshlrev_b64 v[130:131], 11, v[192:193]
	v_lshl_add_u64 v[130:131], v[132:133], 0, v[130:131]
	global_load_dwordx4 v[216:219], v[130:131], off
	v_or_b32_e32 v190, 48, v128
	v_add_u32_e32 v188, 0x80, v128
	v_add_u32_e32 v186, 0x90, v128
	v_add_u32_e32 v184, 0xa0, v128
	v_add_u32_e32 v180, 0xb0, v128
	v_ashrrev_i32_e32 v191, 31, v190
	v_ashrrev_i32_e32 v189, 31, v188
	v_ashrrev_i32_e32 v187, 31, v186
	v_ashrrev_i32_e32 v185, 31, v184
	v_ashrrev_i32_e32 v181, 31, v180
	v_lshlrev_b64 v[128:129], 12, v[128:129]
	v_lshlrev_b64 v[134:135], 11, v[190:191]
	v_lshlrev_b64 v[136:137], 11, v[188:189]
	v_lshlrev_b64 v[138:139], 11, v[186:187]
	v_lshlrev_b64 v[140:141], 11, v[184:185]
	v_lshlrev_b64 v[142:143], 11, v[180:181]
	v_lshl_add_u64 v[128:129], s[62:63], 0, v[128:129]
	v_lshl_add_u64 v[134:135], v[132:133], 0, v[134:135]
	v_lshl_add_u64 v[136:137], v[132:133], 0, v[136:137]
	v_lshl_add_u64 v[138:139], v[132:133], 0, v[138:139]
	v_lshl_add_u64 v[230:231], v[132:133], 0, v[140:141]
	v_lshl_add_u64 v[232:233], v[132:133], 0, v[142:143]
	v_lshl_add_u64 v[234:235], v[128:129], 0, v[182:183]
	global_load_dwordx4 v[220:223], v[130:131], off offset:256
	global_load_dwordx4 v[224:227], v[134:135], off
	global_load_dwordx4 v[160:163], v[134:135], off offset:256
	global_load_dwordx4 v[156:159], v[136:137], off
	global_load_dwordx4 v[152:155], v[136:137], off offset:256
	global_load_dwordx4 v[148:151], v[138:139], off
	global_load_dwordx4 v[144:147], v[138:139], off offset:256
	global_load_dwordx4 v[140:143], v[230:231], off
	s_nop 0
	global_load_dwordx4 v[136:139], v[230:231], off offset:256
	global_load_dwordx4 v[132:135], v[232:233], off
	global_load_dwordx4 v[128:131], v[232:233], off offset:256
	s_and_b64 vcc, exec, s[0:1]
	s_mov_b64 s[0:1], -1
	s_waitcnt vmcnt(0)
	v_lshlrev_b32_e32 v230, 16, v200
	v_and_b32_e32 v231, 0xffff0000, v200
	v_lshlrev_b32_e32 v200, 16, v201
	v_and_b32_e32 v201, 0xffff0000, v201
	v_lshlrev_b32_e32 v238, 16, v206
	v_and_b32_e32 v239, 0xffff0000, v206
	v_lshlrev_b32_e32 v232, 16, v202
	v_and_b32_e32 v233, 0xffff0000, v202
	v_lshlrev_b32_e32 v202, 16, v203
	v_and_b32_e32 v203, 0xffff0000, v203
	v_lshlrev_b32_e32 v236, 16, v204
	v_and_b32_e32 v237, 0xffff0000, v204
	v_lshlrev_b32_e32 v204, 16, v205
	v_and_b32_e32 v205, 0xffff0000, v205
	v_lshlrev_b32_e32 v206, 16, v207
	v_and_b32_e32 v207, 0xffff0000, v207
	v_pk_fma_f32 v[126:127], v[126:127], 0.5, v[200:201] op_sel_hi:[1,0,1]
	v_pk_fma_f32 v[124:125], v[124:125], 0.5, v[230:231] op_sel_hi:[1,0,1]
	v_pk_fma_f32 v[112:113], v[112:113], 0.5, v[238:239] op_sel_hi:[1,0,1]
	v_pk_fma_f32 v[122:123], v[122:123], 0.5, v[202:203] op_sel_hi:[1,0,1]
	v_pk_fma_f32 v[120:121], v[120:121], 0.5, v[232:233] op_sel_hi:[1,0,1]
	v_pk_fma_f32 v[118:119], v[118:119], 0.5, v[204:205] op_sel_hi:[1,0,1]
	v_pk_fma_f32 v[116:117], v[116:117], 0.5, v[236:237] op_sel_hi:[1,0,1]
	v_pk_fma_f32 v[114:115], v[114:115], 0.5, v[206:207] op_sel_hi:[1,0,1]
	global_store_dwordx4 v[234:235], v[124:127], off
	global_store_dwordx4 v[234:235], v[120:123], off offset:16
	global_store_dwordx4 v[234:235], v[116:119], off offset:512
	global_store_dwordx4 v[234:235], v[112:115], off offset:528
	v_lshlrev_b32_e32 v200, 16, v208
	v_and_b32_e32 v201, 0xffff0000, v208
	v_lshlrev_b32_e32 v112, 16, v210
	v_and_b32_e32 v113, 0xffff0000, v210
	v_pk_fma_f32 v[104:105], v[104:105], 0.5, v[112:113] op_sel_hi:[1,0,1]
	v_lshlrev_b64 v[112:113], 12, v[228:229]
	v_lshlrev_b32_e32 v202, 16, v209
	v_and_b32_e32 v203, 0xffff0000, v209
	v_lshlrev_b32_e32 v114, 16, v211
	v_and_b32_e32 v115, 0xffff0000, v211
	v_lshl_add_u64 v[112:113], s[62:63], 0, v[112:113]
	v_pk_fma_f32 v[110:111], v[110:111], 0.5, v[202:203] op_sel_hi:[1,0,1]
	v_pk_fma_f32 v[108:109], v[108:109], 0.5, v[200:201] op_sel_hi:[1,0,1]
	v_pk_fma_f32 v[106:107], v[106:107], 0.5, v[114:115] op_sel_hi:[1,0,1]
	v_lshl_add_u64 v[112:113], v[112:113], 0, v[182:183]
	global_store_dwordx4 v[112:113], v[108:111], off
	global_store_dwordx4 v[112:113], v[104:107], off offset:16
	s_nop 0
	v_lshlrev_b32_e32 v108, 16, v214
	v_lshlrev_b32_e32 v104, 16, v212
	v_and_b32_e32 v105, 0xffff0000, v212
	v_lshlrev_b32_e32 v106, 16, v213
	v_and_b32_e32 v107, 0xffff0000, v213
	v_and_b32_e32 v109, 0xffff0000, v214
	v_lshlrev_b32_e32 v110, 16, v215
	v_and_b32_e32 v111, 0xffff0000, v215
	v_pk_fma_f32 v[102:103], v[102:103], 0.5, v[106:107] op_sel_hi:[1,0,1]
	v_pk_fma_f32 v[100:101], v[100:101], 0.5, v[104:105] op_sel_hi:[1,0,1]
	v_pk_fma_f32 v[92:93], v[92:93], 0.5, v[108:109] op_sel_hi:[1,0,1]
	v_pk_fma_f32 v[94:95], v[94:95], 0.5, v[110:111] op_sel_hi:[1,0,1]
	global_store_dwordx4 v[112:113], v[100:103], off offset:512
	global_store_dwordx4 v[112:113], v[92:95], off offset:528
	s_nop 0
	v_lshlrev_b32_e32 v100, 16, v218
	v_lshlrev_b32_e32 v92, 16, v216
	v_and_b32_e32 v93, 0xffff0000, v216
	v_pk_fma_f32 v[92:93], v[96:97], 0.5, v[92:93] op_sel_hi:[1,0,1]
	v_lshlrev_b64 v[96:97], 12, v[192:193]
	v_lshlrev_b32_e32 v94, 16, v217
	v_and_b32_e32 v95, 0xffff0000, v217
	v_and_b32_e32 v101, 0xffff0000, v218
	v_lshlrev_b32_e32 v102, 16, v219
	v_and_b32_e32 v103, 0xffff0000, v219
	v_lshl_add_u64 v[96:97], s[62:63], 0, v[96:97]
	v_pk_fma_f32 v[94:95], v[98:99], 0.5, v[94:95] op_sel_hi:[1,0,1]
	v_pk_fma_f32 v[90:91], v[90:91], 0.5, v[102:103] op_sel_hi:[1,0,1]
	v_pk_fma_f32 v[88:89], v[88:89], 0.5, v[100:101] op_sel_hi:[1,0,1]
	v_lshl_add_u64 v[96:97], v[96:97], 0, v[182:183]
	global_store_dwordx4 v[96:97], v[92:95], off
	global_store_dwordx4 v[96:97], v[88:91], off offset:16
	s_nop 0
	v_lshlrev_b32_e32 v92, 16, v222
	v_lshlrev_b32_e32 v88, 16, v220
	v_and_b32_e32 v89, 0xffff0000, v220
	v_lshlrev_b32_e32 v90, 16, v221
	v_and_b32_e32 v91, 0xffff0000, v221
	v_and_b32_e32 v93, 0xffff0000, v222
	v_lshlrev_b32_e32 v94, 16, v223
	v_and_b32_e32 v95, 0xffff0000, v223
	v_pk_fma_f32 v[86:87], v[86:87], 0.5, v[90:91] op_sel_hi:[1,0,1]
	v_pk_fma_f32 v[84:85], v[84:85], 0.5, v[88:89] op_sel_hi:[1,0,1]
	v_pk_fma_f32 v[76:77], v[76:77], 0.5, v[92:93] op_sel_hi:[1,0,1]
	v_pk_fma_f32 v[78:79], v[78:79], 0.5, v[94:95] op_sel_hi:[1,0,1]
	global_store_dwordx4 v[96:97], v[84:87], off offset:512
	global_store_dwordx4 v[96:97], v[76:79], off offset:528
	s_nop 0
	v_lshlrev_b32_e32 v84, 16, v226
	v_lshlrev_b32_e32 v76, 16, v224
	v_and_b32_e32 v77, 0xffff0000, v224
	v_pk_fma_f32 v[76:77], v[80:81], 0.5, v[76:77] op_sel_hi:[1,0,1]
	v_lshlrev_b64 v[80:81], 12, v[190:191]
	v_lshlrev_b32_e32 v78, 16, v225
	v_and_b32_e32 v79, 0xffff0000, v225
	v_and_b32_e32 v85, 0xffff0000, v226
	v_lshlrev_b32_e32 v86, 16, v227
	v_and_b32_e32 v87, 0xffff0000, v227
	v_lshl_add_u64 v[80:81], s[62:63], 0, v[80:81]
	v_pk_fma_f32 v[78:79], v[82:83], 0.5, v[78:79] op_sel_hi:[1,0,1]
	v_pk_fma_f32 v[74:75], v[74:75], 0.5, v[86:87] op_sel_hi:[1,0,1]
	v_pk_fma_f32 v[72:73], v[72:73], 0.5, v[84:85] op_sel_hi:[1,0,1]
	v_lshl_add_u64 v[80:81], v[80:81], 0, v[182:183]
	global_store_dwordx4 v[80:81], v[76:79], off
	global_store_dwordx4 v[80:81], v[72:75], off offset:16
	s_nop 0
	v_lshlrev_b32_e32 v76, 16, v162
	v_lshlrev_b32_e32 v72, 16, v160
	v_and_b32_e32 v73, 0xffff0000, v160
	v_lshlrev_b32_e32 v74, 16, v161
	v_and_b32_e32 v75, 0xffff0000, v161
	v_and_b32_e32 v77, 0xffff0000, v162
	v_lshlrev_b32_e32 v78, 16, v163
	v_and_b32_e32 v79, 0xffff0000, v163
	v_pk_fma_f32 v[70:71], v[70:71], 0.5, v[74:75] op_sel_hi:[1,0,1]
	v_pk_fma_f32 v[68:69], v[68:69], 0.5, v[72:73] op_sel_hi:[1,0,1]
	v_pk_fma_f32 v[64:65], v[64:65], 0.5, v[76:77] op_sel_hi:[1,0,1]
	v_pk_fma_f32 v[66:67], v[66:67], 0.5, v[78:79] op_sel_hi:[1,0,1]
	global_store_dwordx4 v[80:81], v[68:71], off offset:512
	global_store_dwordx4 v[80:81], v[64:67], off offset:528
	s_nop 0
	v_lshlrev_b32_e32 v68, 16, v158
	v_lshlrev_b32_e32 v64, 16, v156
	v_and_b32_e32 v65, 0xffff0000, v156
	v_pk_fma_f32 v[60:61], v[60:61], 0.5, v[64:65] op_sel_hi:[1,0,1]
	v_lshlrev_b64 v[64:65], 12, v[188:189]
	v_lshlrev_b32_e32 v66, 16, v157
	v_and_b32_e32 v67, 0xffff0000, v157
	v_and_b32_e32 v69, 0xffff0000, v158
	v_lshlrev_b32_e32 v70, 16, v159
	v_and_b32_e32 v71, 0xffff0000, v159
	v_lshl_add_u64 v[64:65], s[62:63], 0, v[64:65]
	v_pk_fma_f32 v[62:63], v[62:63], 0.5, v[66:67] op_sel_hi:[1,0,1]
	v_pk_fma_f32 v[58:59], v[58:59], 0.5, v[70:71] op_sel_hi:[1,0,1]
	v_pk_fma_f32 v[56:57], v[56:57], 0.5, v[68:69] op_sel_hi:[1,0,1]
	v_lshl_add_u64 v[64:65], v[64:65], 0, v[182:183]
	global_store_dwordx4 v[64:65], v[60:63], off
	global_store_dwordx4 v[64:65], v[56:59], off offset:16
	s_nop 0
	v_lshlrev_b32_e32 v60, 16, v154
	v_lshlrev_b32_e32 v56, 16, v152
	v_and_b32_e32 v57, 0xffff0000, v152
	v_lshlrev_b32_e32 v58, 16, v153
	v_and_b32_e32 v59, 0xffff0000, v153
	v_and_b32_e32 v61, 0xffff0000, v154
	v_lshlrev_b32_e32 v62, 16, v155
	v_and_b32_e32 v63, 0xffff0000, v155
	v_pk_fma_f32 v[54:55], v[54:55], 0.5, v[58:59] op_sel_hi:[1,0,1]
	v_pk_fma_f32 v[52:53], v[52:53], 0.5, v[56:57] op_sel_hi:[1,0,1]
	v_pk_fma_f32 v[44:45], v[44:45], 0.5, v[60:61] op_sel_hi:[1,0,1]
	v_pk_fma_f32 v[46:47], v[46:47], 0.5, v[62:63] op_sel_hi:[1,0,1]
	global_store_dwordx4 v[64:65], v[52:55], off offset:512
	global_store_dwordx4 v[64:65], v[44:47], off offset:528
	s_nop 0
	v_lshlrev_b32_e32 v52, 16, v150
	v_lshlrev_b32_e32 v44, 16, v148
	v_and_b32_e32 v45, 0xffff0000, v148
	v_pk_fma_f32 v[44:45], v[48:49], 0.5, v[44:45] op_sel_hi:[1,0,1]
	v_lshlrev_b64 v[48:49], 12, v[186:187]
	v_lshlrev_b32_e32 v46, 16, v149
	v_and_b32_e32 v47, 0xffff0000, v149
	v_and_b32_e32 v53, 0xffff0000, v150
	v_lshlrev_b32_e32 v54, 16, v151
	v_and_b32_e32 v55, 0xffff0000, v151
	v_lshl_add_u64 v[48:49], s[62:63], 0, v[48:49]
	v_pk_fma_f32 v[46:47], v[50:51], 0.5, v[46:47] op_sel_hi:[1,0,1]
	v_pk_fma_f32 v[42:43], v[42:43], 0.5, v[54:55] op_sel_hi:[1,0,1]
	v_pk_fma_f32 v[40:41], v[40:41], 0.5, v[52:53] op_sel_hi:[1,0,1]
	v_lshl_add_u64 v[48:49], v[48:49], 0, v[182:183]
	global_store_dwordx4 v[48:49], v[44:47], off
	global_store_dwordx4 v[48:49], v[40:43], off offset:16
	s_nop 0
	v_lshlrev_b32_e32 v44, 16, v146
	v_lshlrev_b32_e32 v40, 16, v144
	v_and_b32_e32 v41, 0xffff0000, v144
	v_lshlrev_b32_e32 v42, 16, v145
	v_and_b32_e32 v43, 0xffff0000, v145
	v_and_b32_e32 v45, 0xffff0000, v146
	v_lshlrev_b32_e32 v46, 16, v147
	v_and_b32_e32 v47, 0xffff0000, v147
	v_pk_fma_f32 v[38:39], v[38:39], 0.5, v[42:43] op_sel_hi:[1,0,1]
	v_pk_fma_f32 v[36:37], v[36:37], 0.5, v[40:41] op_sel_hi:[1,0,1]
	v_pk_fma_f32 v[28:29], v[28:29], 0.5, v[44:45] op_sel_hi:[1,0,1]
	v_pk_fma_f32 v[30:31], v[30:31], 0.5, v[46:47] op_sel_hi:[1,0,1]
	global_store_dwordx4 v[48:49], v[36:39], off offset:512
	global_store_dwordx4 v[48:49], v[28:31], off offset:528
	s_nop 0
	v_lshlrev_b32_e32 v36, 16, v142
	v_lshlrev_b32_e32 v28, 16, v140
	v_and_b32_e32 v29, 0xffff0000, v140
	v_pk_fma_f32 v[28:29], v[32:33], 0.5, v[28:29] op_sel_hi:[1,0,1]
	v_lshlrev_b64 v[32:33], 12, v[184:185]
	v_lshlrev_b32_e32 v30, 16, v141
	v_and_b32_e32 v31, 0xffff0000, v141
	v_and_b32_e32 v37, 0xffff0000, v142
	v_lshlrev_b32_e32 v38, 16, v143
	v_and_b32_e32 v39, 0xffff0000, v143
	v_lshl_add_u64 v[32:33], s[62:63], 0, v[32:33]
	v_pk_fma_f32 v[30:31], v[34:35], 0.5, v[30:31] op_sel_hi:[1,0,1]
	v_pk_fma_f32 v[26:27], v[26:27], 0.5, v[38:39] op_sel_hi:[1,0,1]
	v_pk_fma_f32 v[24:25], v[24:25], 0.5, v[36:37] op_sel_hi:[1,0,1]
	v_lshl_add_u64 v[32:33], v[32:33], 0, v[182:183]
	global_store_dwordx4 v[32:33], v[28:31], off
	global_store_dwordx4 v[32:33], v[24:27], off offset:16
	s_nop 0
	v_lshlrev_b32_e32 v28, 16, v138
	v_lshlrev_b32_e32 v24, 16, v136
	v_and_b32_e32 v25, 0xffff0000, v136
	v_lshlrev_b32_e32 v26, 16, v137
	v_and_b32_e32 v27, 0xffff0000, v137
	v_and_b32_e32 v29, 0xffff0000, v138
	v_lshlrev_b32_e32 v30, 16, v139
	v_and_b32_e32 v31, 0xffff0000, v139
	v_pk_fma_f32 v[22:23], v[22:23], 0.5, v[26:27] op_sel_hi:[1,0,1]
	v_pk_fma_f32 v[20:21], v[20:21], 0.5, v[24:25] op_sel_hi:[1,0,1]
	v_pk_fma_f32 v[12:13], v[12:13], 0.5, v[28:29] op_sel_hi:[1,0,1]
	v_pk_fma_f32 v[14:15], v[14:15], 0.5, v[30:31] op_sel_hi:[1,0,1]
	global_store_dwordx4 v[32:33], v[20:23], off offset:512
	global_store_dwordx4 v[32:33], v[12:15], off offset:528
	s_nop 0
	v_lshlrev_b32_e32 v20, 16, v134
	v_lshlrev_b32_e32 v12, 16, v132
	v_and_b32_e32 v13, 0xffff0000, v132
	v_pk_fma_f32 v[12:13], v[16:17], 0.5, v[12:13] op_sel_hi:[1,0,1]
	v_lshlrev_b64 v[16:17], 12, v[180:181]
	v_lshlrev_b32_e32 v14, 16, v133
	v_and_b32_e32 v15, 0xffff0000, v133
	v_and_b32_e32 v21, 0xffff0000, v134
	v_lshlrev_b32_e32 v22, 16, v135
	v_and_b32_e32 v23, 0xffff0000, v135
	v_lshl_add_u64 v[16:17], s[62:63], 0, v[16:17]
	v_pk_fma_f32 v[14:15], v[18:19], 0.5, v[14:15] op_sel_hi:[1,0,1]
	v_pk_fma_f32 v[10:11], v[10:11], 0.5, v[22:23] op_sel_hi:[1,0,1]
	v_pk_fma_f32 v[8:9], v[8:9], 0.5, v[20:21] op_sel_hi:[1,0,1]
	v_lshl_add_u64 v[16:17], v[16:17], 0, v[182:183]
	global_store_dwordx4 v[16:17], v[12:15], off
	global_store_dwordx4 v[16:17], v[8:11], off offset:16
	s_nop 0
	v_lshlrev_b32_e32 v12, 16, v130
	v_lshlrev_b32_e32 v8, 16, v128
	v_and_b32_e32 v9, 0xffff0000, v128
	v_lshlrev_b32_e32 v10, 16, v129
	v_and_b32_e32 v11, 0xffff0000, v129
	v_and_b32_e32 v13, 0xffff0000, v130
	v_lshlrev_b32_e32 v14, 16, v131
	v_and_b32_e32 v15, 0xffff0000, v131
	v_pk_fma_f32 v[6:7], v[6:7], 0.5, v[10:11] op_sel_hi:[1,0,1]
	v_pk_fma_f32 v[4:5], v[4:5], 0.5, v[8:9] op_sel_hi:[1,0,1]
	v_pk_fma_f32 v[2:3], v[2:3], 0.5, v[14:15] op_sel_hi:[1,0,1]
	v_pk_fma_f32 v[0:1], v[0:1], 0.5, v[12:13] op_sel_hi:[1,0,1]
	global_store_dwordx4 v[16:17], v[4:7], off offset:512
	global_store_dwordx4 v[16:17], v[0:3], off offset:528
	s_cbranch_vccnz .LBB0_2329
	s_andn2_b64 vcc, exec, s[6:7]
	s_cbranch_vccnz .LBB0_2328
	s_barrier
	s_branch .LBB0_2328
